# pool_d sample rows: the four window groups spread over workgroups 0..31 (one load round trip each) instead of four serial round trips on workgroups 0..7
# speedup vs baseline: 1.0098x; 1.0098x over previous
; __device__ __forceinline__ float bflo(unsigned w) { return __uint_as_float(w << 16); }
; __device__ __forceinline__ float bfhi(unsigned w) { return __uint_as_float(w & 0xffff0000u); }
; template <int W>
; __device__ __forceinline__ void pool_item(const Params& p, const bf16_t* PROJ, bf16_t* D, int r, int c0) {
;     float sum[8], uu[8];
;     const u32x4 v0 = *(const u32x4*)(PROJ + (size_t)r * NQ + c0);
;     uu[0] = bflo(v0.x); uu[1] = bfhi(v0.x); uu[2] = bflo(v0.y); uu[3] = bfhi(v0.y); uu[4] = bflo(v0.z); uu[5] = bfhi(v0.z); uu[6] = bflo(v0.w); uu[7] = bfhi(v0.w);
; #pragma unroll
;     for (int j = 0; j < 8; ++j) sum[j] = uu[j];
;     float cnt;
;     if (r < MP) {
;         const int t = r & 2047; cnt = (float)((t + 1 < W) ? (t + 1) : W);
;         u32x4 v[W - 1];
; #pragma unroll
;         for (int i = 1; i < W; ++i) v[i - 1] = *(const u32x4*)(PROJ + (size_t)(r - (i <= t ? i : 0)) * NQ + c0);
; #pragma unroll
;         for (int i = 1; i < W; ++i) acc8(sum, v[i - 1], (i <= t) ? 1.f : 0.f);
; __device__ __forceinline__ void phase_pool_d(const Params& p, int wave_s) {
;     const bf16_t* PROJ = (const bf16_t*)(p.ws + WS_PROJ); bf16_t* D = (bf16_t*)(p.ws + WS_D);
;     const int total = MR * 32;
;     const int tid = opaque_tid(wave_s);
;     for (int idx = blockIdx.x * 512 + tid; idx < total; idx += gridDim.x * 512) {
;         const int r = idx >> 5, ch = idx & 31;
;         pool_item<2>(p, PROJ, D, r, ch * 8);
;         pool_item<4>(p, PROJ, D, r, 256 + ch * 8);
;         pool_item<8>(p, PROJ, D, r, 512 + ch * 8);
;         pool_item<16>(p, PROJ, D, r, 768 + ch * 8);
;     }
.LBB0_641:
	s_cmp_lt_i32 s18, 3
	s_cselect_b64 s[4:5], -1, 0
	s_and_b64 s[26:27], s[4:5], s[0:1]
	s_andn2_b64 vcc, exec, s[26:27]
	s_cbranch_vccnz .LBB0_787
	s_mov_b32 s32, 0
	s_add_i32 s79, s2, 0x600
	s_mov_b64 exec, -1
	s_add_u32 s28, s22, 0xa6aa000
	s_addc_u32 s29, s23, 0
	s_add_u32 s84, s22, 0x64aa000
	s_addc_u32 s85, s23, 0
	v_mbcnt_lo_u32_b32 v0, -1, 0
	v_mbcnt_hi_u32_b32 v0, -1, v0
	v_or_b32_e32 v1, s24, v0
	v_lshl_add_u32 v2, s2, 9, v1
	s_mov_b32 s86, 0
	v_lshrrev_b32_e32 v3, 5, v2
	v_lshl_or_b32 v3, v3, 1, 1
	v_and_b32_e32 v4, 0x7ff, v3
	v_and_b32_e32 v5, 31, v2
	v_lshlrev_b32_e32 v5, 4, v5
	v_mul_u32_u24_e32 v6, 0x4800, v3
	v_add_u32_e32 v6, v6, v5
	v_lshl_add_u32 v7, v3, 11, v5
	v_mov_b32_e32 v16, v6
	v_mov_b32_e32 v33, 1.0
	v_cmp_le_u32_e32 vcc, 1, v4
	v_mov_b32_e32 v8, 0x4800
	s_nop 0
	v_cndmask_b32_e32 v8, 0, v8, vcc
	v_sub_u32_e32 v17, v6, v8
	v_cndmask_b32_e64 v34, 0, 1.0, vcc
	v_cmp_le_u32_e32 vcc, 2, v4
	v_mov_b32_e32 v8, 0x9000
	s_nop 0
	v_cndmask_b32_e32 v8, 0, v8, vcc
	v_sub_u32_e32 v18, v6, v8
	v_cndmask_b32_e64 v35, 0, 1.0, vcc
	v_cmp_le_u32_e32 vcc, 3, v4
	v_mov_b32_e32 v8, 0xd800
	s_nop 0
	v_cndmask_b32_e32 v8, 0, v8, vcc
	v_sub_u32_e32 v19, v6, v8
	v_cndmask_b32_e64 v36, 0, 1.0, vcc
	v_cmp_le_u32_e32 vcc, 4, v4
	v_mov_b32_e32 v8, 0x12000
	s_nop 0
	v_cndmask_b32_e32 v8, 0, v8, vcc
	v_sub_u32_e32 v20, v6, v8
	v_cndmask_b32_e64 v37, 0, 1.0, vcc
	v_cmp_le_u32_e32 vcc, 5, v4
	v_mov_b32_e32 v8, 0x16800
	s_nop 0
	v_cndmask_b32_e32 v8, 0, v8, vcc
	v_sub_u32_e32 v21, v6, v8
	v_cndmask_b32_e64 v38, 0, 1.0, vcc
	v_cmp_le_u32_e32 vcc, 6, v4
	v_mov_b32_e32 v8, 0x1b000
	s_nop 0
	v_cndmask_b32_e32 v8, 0, v8, vcc
	v_sub_u32_e32 v22, v6, v8
	v_cndmask_b32_e64 v39, 0, 1.0, vcc
	v_cmp_le_u32_e32 vcc, 7, v4
	v_mov_b32_e32 v8, 0x1f800
	s_nop 0
	v_cndmask_b32_e32 v8, 0, v8, vcc
	v_sub_u32_e32 v23, v6, v8
	v_cndmask_b32_e64 v40, 0, 1.0, vcc
	v_cmp_le_u32_e32 vcc, 8, v4
	v_mov_b32_e32 v8, 0x24000
	s_nop 0
	v_cndmask_b32_e32 v8, 0, v8, vcc
	v_sub_u32_e32 v24, v6, v8
	v_cndmask_b32_e64 v41, 0, 1.0, vcc
	v_cmp_le_u32_e32 vcc, 9, v4
	v_mov_b32_e32 v8, 0x28800
	s_nop 0
	v_cndmask_b32_e32 v8, 0, v8, vcc
	v_sub_u32_e32 v25, v6, v8
	v_cndmask_b32_e64 v42, 0, 1.0, vcc
	v_cmp_le_u32_e32 vcc, 10, v4
	v_mov_b32_e32 v8, 0x2d000
	s_nop 0
	v_cndmask_b32_e32 v8, 0, v8, vcc
	v_sub_u32_e32 v26, v6, v8
	v_cndmask_b32_e64 v43, 0, 1.0, vcc
	v_cmp_le_u32_e32 vcc, 11, v4
	v_mov_b32_e32 v8, 0x31800
	s_nop 0
	v_cndmask_b32_e32 v8, 0, v8, vcc
	v_sub_u32_e32 v27, v6, v8
	v_cndmask_b32_e64 v44, 0, 1.0, vcc
	v_cmp_le_u32_e32 vcc, 12, v4
	v_mov_b32_e32 v8, 0x36000
	s_nop 0
	v_cndmask_b32_e32 v8, 0, v8, vcc
	v_sub_u32_e32 v28, v6, v8
	v_cndmask_b32_e64 v45, 0, 1.0, vcc
	v_cmp_le_u32_e32 vcc, 13, v4
	v_mov_b32_e32 v8, 0x3a800
	s_nop 0
	v_cndmask_b32_e32 v8, 0, v8, vcc
	v_sub_u32_e32 v29, v6, v8
	v_cndmask_b32_e64 v46, 0, 1.0, vcc
	v_cmp_le_u32_e32 vcc, 14, v4
	v_mov_b32_e32 v8, 0x3f000
	s_nop 0
	v_cndmask_b32_e32 v8, 0, v8, vcc
	v_sub_u32_e32 v30, v6, v8
	v_cndmask_b32_e64 v47, 0, 1.0, vcc
	v_cmp_le_u32_e32 vcc, 15, v4
	v_mov_b32_e32 v8, 0x43800
	s_nop 0
	v_cndmask_b32_e32 v8, 0, v8, vcc
	v_sub_u32_e32 v31, v6, v8
	v_cndmask_b32_e64 v48, 0, 1.0, vcc
	v_cmp_le_u32_e32 vcc, 16, v4
	v_mov_b32_e32 v8, 0x48000
	s_nop 0
	v_cndmask_b32_e32 v8, 0, v8, vcc
	v_sub_u32_e32 v32, v6, v8
	v_cndmask_b32_e64 v49, 0, 1.0, vcc
	global_load_dwordx4 v[64:67], v16, s[28:29]
	global_load_dwordx4 v[68:71], v17, s[28:29]
	global_load_dwordx4 v[72:75], v18, s[28:29]
	global_load_dwordx4 v[76:79], v16, s[28:29] offset:512
	global_load_dwordx4 v[80:83], v17, s[28:29] offset:512
	global_load_dwordx4 v[84:87], v18, s[28:29] offset:512
	global_load_dwordx4 v[88:91], v19, s[28:29] offset:512
	global_load_dwordx4 v[92:95], v20, s[28:29] offset:512
	global_load_dwordx4 v[96:99], v16, s[28:29] offset:1024
	global_load_dwordx4 v[100:103], v17, s[28:29] offset:1024
	global_load_dwordx4 v[104:107], v18, s[28:29] offset:1024
	global_load_dwordx4 v[108:111], v19, s[28:29] offset:1024
	global_load_dwordx4 v[112:115], v20, s[28:29] offset:1024
	global_load_dwordx4 v[116:119], v21, s[28:29] offset:1024
	global_load_dwordx4 v[120:123], v22, s[28:29] offset:1024
	global_load_dwordx4 v[124:127], v23, s[28:29] offset:1024
	global_load_dwordx4 v[128:131], v24, s[28:29] offset:1024
	global_load_dwordx4 v[132:135], v16, s[28:29] offset:1536
	global_load_dwordx4 v[136:139], v17, s[28:29] offset:1536
	global_load_dwordx4 v[140:143], v18, s[28:29] offset:1536
	global_load_dwordx4 v[144:147], v19, s[28:29] offset:1536
	global_load_dwordx4 v[148:151], v20, s[28:29] offset:1536
	global_load_dwordx4 v[152:155], v21, s[28:29] offset:1536
	global_load_dwordx4 v[156:159], v22, s[28:29] offset:1536
	global_load_dwordx4 v[160:163], v23, s[28:29] offset:1536
	global_load_dwordx4 v[164:167], v24, s[28:29] offset:1536
	global_load_dwordx4 v[168:171], v25, s[28:29] offset:1536
	global_load_dwordx4 v[172:175], v26, s[28:29] offset:1536
	global_load_dwordx4 v[176:179], v27, s[28:29] offset:1536
	global_load_dwordx4 v[180:183], v28, s[28:29] offset:1536
	global_load_dwordx4 v[184:187], v29, s[28:29] offset:1536
	global_load_dwordx4 v[188:191], v30, s[28:29] offset:1536
	global_load_dwordx4 v[192:195], v31, s[28:29] offset:1536
	global_load_dwordx4 v[196:199], v32, s[28:29] offset:1536
	v_add_u32_e32 v9, 1, v4
	v_min_u32_e32 v10, 2, v9
	v_cvt_f32_u32_e32 v11, v10
	v_div_scale_f32 v200, s[88:89], v11, v11, 1.0
	v_rcp_f32_e32 v201, v200
	v_div_scale_f32 v202, vcc, 1.0, v11, 1.0
	v_fma_f32 v203, -v200, v201, 1.0
	v_fmac_f32_e32 v201, v203, v201
	v_mul_f32_e32 v203, v202, v201
	v_fma_f32 v204, -v200, v203, v202
	v_fmac_f32_e32 v203, v204, v201
; __device__ __forceinline__ unsigned pk2(float lo, float hi) { const f32x2_t v = {lo, hi}; const bf16x2_t b = __builtin_convertvector(v, bf16x2_t); return __builtin_bit_cast(unsigned, b); }
; template <int W>
; __device__ __forceinline__ void pool_item(const Params& p, const bf16_t* PROJ, bf16_t* D, int r, int c0) {
;     ...
;         const int t = r & 2047; cnt = (float)((t + 1 < W) ? (t + 1) : W);
;         u32x4 v[W - 1];
; #pragma unroll
;         for (int i = 1; i < W; ++i) v[i - 1] = *(const u32x4*)(PROJ + (size_t)(r - (i <= t ? i : 0)) * NQ + c0);
; #pragma unroll
;         for (int i = 1; i < W; ++i) acc8(sum, v[i - 1], (i <= t) ? 1.f : 0.f);
;     } else {
;         const int s = r - MP; cnt = (float)W; const float* sp = p.in[4] + (size_t)s * 15 * 1024 + c0;
;         f32x4 a[W - 1], b[W - 1];
; #pragma unroll
;         for (int i = 0; i < W - 1; ++i) { a[i] = *(const f32x4*)(sp + (size_t)(14 - i) * 1024); b[i] = *(const f32x4*)(sp + (size_t)(14 - i) * 1024 + 4); }
; #pragma unroll
;         for (int i = 0; i < W - 1; ++i) { sum[0] += a[i].x; sum[1] += a[i].y; sum[2] += a[i].z; sum[3] += a[i].w; sum[4] += b[i].x; sum[5] += b[i].y; sum[6] += b[i].z; sum[7] += b[i].w; }
;     }
;     const float inv = 1.0f / cnt; u32x4 o;
;     o.x = pk2(sum[0] * inv - uu[0], sum[1] * inv - uu[1]); o.y = pk2(sum[2] * inv - uu[2], sum[3] * inv - uu[3]);
;     o.z = pk2(sum[4] * inv - uu[4], sum[5] * inv - uu[5]); o.w = pk2(sum[6] * inv - uu[6], sum[7] * inv - uu[7]);
;     *(u32x4*)(D + (size_t)r * 1024 + c0) = o;
	v_fma_f32 v200, -v200, v203, v202
	v_div_fmas_f32 v200, v200, v201, v203
	v_div_fixup_f32 v50, v200, v11, 1.0
	v_min_u32_e32 v10, 2, v4
	v_cvt_f32_u32_e32 v11, v10
	v_div_scale_f32 v200, s[88:89], v11, v11, 1.0
	v_rcp_f32_e32 v201, v200
	v_div_scale_f32 v202, vcc, 1.0, v11, 1.0
	v_fma_f32 v203, -v200, v201, 1.0
	v_fmac_f32_e32 v201, v203, v201
	v_mul_f32_e32 v203, v202, v201
	v_fma_f32 v204, -v200, v203, v202
	v_fmac_f32_e32 v203, v204, v201
	v_fma_f32 v200, -v200, v203, v202
	v_div_fmas_f32 v200, v200, v201, v203
	v_div_fixup_f32 v54, v200, v11, 1.0
	v_min_u32_e32 v10, 4, v9
	v_cvt_f32_u32_e32 v11, v10
	v_div_scale_f32 v200, s[88:89], v11, v11, 1.0
	v_rcp_f32_e32 v201, v200
	v_div_scale_f32 v202, vcc, 1.0, v11, 1.0
	v_fma_f32 v203, -v200, v201, 1.0
	v_fmac_f32_e32 v201, v203, v201
	v_mul_f32_e32 v203, v202, v201
	v_fma_f32 v204, -v200, v203, v202
	v_fmac_f32_e32 v203, v204, v201
	v_fma_f32 v200, -v200, v203, v202
	v_div_fmas_f32 v200, v200, v201, v203
	v_div_fixup_f32 v51, v200, v11, 1.0
	v_min_u32_e32 v10, 4, v4
	v_cvt_f32_u32_e32 v11, v10
	v_div_scale_f32 v200, s[88:89], v11, v11, 1.0
	v_rcp_f32_e32 v201, v200
	v_div_scale_f32 v202, vcc, 1.0, v11, 1.0
	v_fma_f32 v203, -v200, v201, 1.0
	v_fmac_f32_e32 v201, v203, v201
	v_mul_f32_e32 v203, v202, v201
	v_fma_f32 v204, -v200, v203, v202
	v_fmac_f32_e32 v203, v204, v201
	v_fma_f32 v200, -v200, v203, v202
	v_div_fmas_f32 v200, v200, v201, v203
	v_div_fixup_f32 v55, v200, v11, 1.0
	v_min_u32_e32 v10, 8, v9
	v_cvt_f32_u32_e32 v11, v10
	v_div_scale_f32 v200, s[88:89], v11, v11, 1.0
	v_rcp_f32_e32 v201, v200
	v_div_scale_f32 v202, vcc, 1.0, v11, 1.0
	v_fma_f32 v203, -v200, v201, 1.0
	v_fmac_f32_e32 v201, v203, v201
	v_mul_f32_e32 v203, v202, v201
	v_fma_f32 v204, -v200, v203, v202
	v_fmac_f32_e32 v203, v204, v201
	v_fma_f32 v200, -v200, v203, v202
	v_div_fmas_f32 v200, v200, v201, v203
	v_div_fixup_f32 v52, v200, v11, 1.0
	v_min_u32_e32 v10, 8, v4
	v_cvt_f32_u32_e32 v11, v10
	v_div_scale_f32 v200, s[88:89], v11, v11, 1.0
	v_rcp_f32_e32 v201, v200
	v_div_scale_f32 v202, vcc, 1.0, v11, 1.0
	v_fma_f32 v203, -v200, v201, 1.0
	v_fmac_f32_e32 v201, v203, v201
	v_mul_f32_e32 v203, v202, v201
	v_fma_f32 v204, -v200, v203, v202
	v_fmac_f32_e32 v203, v204, v201
	v_fma_f32 v200, -v200, v203, v202
	v_div_fmas_f32 v200, v200, v201, v203
	v_div_fixup_f32 v56, v200, v11, 1.0
	v_min_u32_e32 v10, 16, v9
	v_cvt_f32_u32_e32 v11, v10
	v_div_scale_f32 v200, s[88:89], v11, v11, 1.0
	v_rcp_f32_e32 v201, v200
	v_div_scale_f32 v202, vcc, 1.0, v11, 1.0
	v_fma_f32 v203, -v200, v201, 1.0
	v_fmac_f32_e32 v201, v203, v201
	v_mul_f32_e32 v203, v202, v201
	v_fma_f32 v204, -v200, v203, v202
	v_fmac_f32_e32 v203, v204, v201
	v_fma_f32 v200, -v200, v203, v202
	v_div_fmas_f32 v200, v200, v201, v203
	v_div_fixup_f32 v53, v200, v11, 1.0
	v_min_u32_e32 v10, 16, v4
	v_cvt_f32_u32_e32 v11, v10
	v_div_scale_f32 v200, s[88:89], v11, v11, 1.0
	v_rcp_f32_e32 v201, v200
	v_div_scale_f32 v202, vcc, 1.0, v11, 1.0
	v_fma_f32 v203, -v200, v201, 1.0
	v_fmac_f32_e32 v201, v203, v201
	v_mul_f32_e32 v203, v202, v201
	v_fma_f32 v204, -v200, v203, v202
	v_fmac_f32_e32 v203, v204, v201
	v_fma_f32 v200, -v200, v203, v202
	v_div_fmas_f32 v200, v200, v201, v203
	v_div_fixup_f32 v57, v200, v11, 1.0
	s_waitcnt vmcnt(31)
	v_lshlrev_b32_e32 v206, 16, v64
	v_and_b32_e32 v207, 0xffff0000, v64
	v_lshlrev_b32_e32 v208, 16, v65
	v_and_b32_e32 v209, 0xffff0000, v65
	v_lshlrev_b32_e32 v210, 16, v66
	v_and_b32_e32 v211, 0xffff0000, v66
	v_lshlrev_b32_e32 v212, 16, v67
	v_and_b32_e32 v213, 0xffff0000, v67
	v_lshlrev_b32_e32 v214, 16, v68
	v_and_b32_e32 v215, 0xffff0000, v68
	v_lshlrev_b32_e32 v216, 16, v69
	v_and_b32_e32 v217, 0xffff0000, v69
	v_lshlrev_b32_e32 v218, 16, v70
	v_and_b32_e32 v219, 0xffff0000, v70
	v_lshlrev_b32_e32 v220, 16, v71
	v_and_b32_e32 v221, 0xffff0000, v71
	v_mov_b32_e32 v222, v206
	v_mov_b32_e32 v230, v214
	v_mov_b32_e32 v223, v207
	v_mov_b32_e32 v231, v215
	v_mov_b32_e32 v224, v208
	v_mov_b32_e32 v232, v216
	v_mov_b32_e32 v225, v209
	v_mov_b32_e32 v233, v217
	v_mov_b32_e32 v226, v210
	v_mov_b32_e32 v234, v218
	v_mov_b32_e32 v227, v211
	v_mov_b32_e32 v235, v219
	v_mov_b32_e32 v228, v212
	v_mov_b32_e32 v236, v220
	v_mov_b32_e32 v229, v213
	v_mov_b32_e32 v237, v221
	v_fmac_f32_e32 v222, v214, v34
	v_fmac_f32_e32 v223, v215, v34
	v_fmac_f32_e32 v224, v216, v34
	v_fmac_f32_e32 v225, v217, v34
	v_fmac_f32_e32 v226, v218, v34
	v_fmac_f32_e32 v227, v219, v34
	v_fmac_f32_e32 v228, v220, v34
	v_fmac_f32_e32 v229, v221, v34
	v_lshlrev_b32_e32 v238, 16, v72
	v_and_b32_e32 v239, 0xffff0000, v72
	v_lshlrev_b32_e32 v240, 16, v73
	v_and_b32_e32 v241, 0xffff0000, v73
	v_lshlrev_b32_e32 v242, 16, v74
	v_and_b32_e32 v243, 0xffff0000, v74
	v_lshlrev_b32_e32 v244, 16, v75
	v_and_b32_e32 v245, 0xffff0000, v75
	v_fmac_f32_e32 v230, v238, v35
	v_fmac_f32_e32 v231, v239, v35
	v_fmac_f32_e32 v232, v240, v35
	v_fmac_f32_e32 v233, v241, v35
	v_fmac_f32_e32 v234, v242, v35
	v_fmac_f32_e32 v235, v243, v35
	v_fmac_f32_e32 v236, v244, v35
	v_fmac_f32_e32 v237, v245, v35
	v_fma_f32 v222, v222, v50, -v206
	v_fma_f32 v230, v230, v54, -v214
	v_fma_f32 v223, v223, v50, -v207
	v_fma_f32 v231, v231, v54, -v215
	v_fma_f32 v224, v224, v50, -v208
	v_fma_f32 v232, v232, v54, -v216
	v_fma_f32 v225, v225, v50, -v209
	v_fma_f32 v233, v233, v54, -v217
	v_fma_f32 v226, v226, v50, -v210
	v_fma_f32 v234, v234, v54, -v218
	v_fma_f32 v227, v227, v50, -v211
	v_fma_f32 v235, v235, v54, -v219
	v_fma_f32 v228, v228, v50, -v212
	v_fma_f32 v236, v236, v54, -v220
	v_fma_f32 v229, v229, v50, -v213
	v_fma_f32 v237, v237, v54, -v221
	v_cvt_pk_bf16_f32 v246, v222, v223
	v_cvt_pk_bf16_f32 v247, v224, v225
	v_cvt_pk_bf16_f32 v248, v226, v227
	v_cvt_pk_bf16_f32 v249, v228, v229
	global_store_dwordx4 v7, v[246:249], s[84:85]
	s_nop 1
	v_cvt_pk_bf16_f32 v250, v230, v231
	v_cvt_pk_bf16_f32 v251, v232, v233
	v_cvt_pk_bf16_f32 v252, v234, v235
	v_cvt_pk_bf16_f32 v253, v236, v237
	global_store_dwordx4 v7, v[250:253], s[84:85] offset:-2048
	s_nop 1
	s_waitcnt vmcnt(28)
; __device__ __forceinline__ unsigned pk2(float lo, float hi) { const f32x2_t v = {lo, hi}; const bf16x2_t b = __builtin_convertvector(v, bf16x2_t); return __builtin_bit_cast(unsigned, b); }
; template <int W>
; __device__ __forceinline__ void pool_item(const Params& p, const bf16_t* PROJ, bf16_t* D, int r, int c0) {
;     ...
;         const int t = r & 2047; cnt = (float)((t + 1 < W) ? (t + 1) : W);
;         u32x4 v[W - 1];
; #pragma unroll
;         for (int i = 1; i < W; ++i) v[i - 1] = *(const u32x4*)(PROJ + (size_t)(r - (i <= t ? i : 0)) * NQ + c0);
; #pragma unroll
;         for (int i = 1; i < W; ++i) acc8(sum, v[i - 1], (i <= t) ? 1.f : 0.f);
;     } else {
;         const int s = r - MP; cnt = (float)W; const float* sp = p.in[4] + (size_t)s * 15 * 1024 + c0;
;         f32x4 a[W - 1], b[W - 1];
; #pragma unroll
;         for (int i = 0; i < W - 1; ++i) { a[i] = *(const f32x4*)(sp + (size_t)(14 - i) * 1024); b[i] = *(const f32x4*)(sp + (size_t)(14 - i) * 1024 + 4); }
; #pragma unroll
;         for (int i = 0; i < W - 1; ++i) { sum[0] += a[i].x; sum[1] += a[i].y; sum[2] += a[i].z; sum[3] += a[i].w; sum[4] += b[i].x; sum[5] += b[i].y; sum[6] += b[i].z; sum[7] += b[i].w; }
;     }
;     const float inv = 1.0f / cnt; u32x4 o;
;     o.x = pk2(sum[0] * inv - uu[0], sum[1] * inv - uu[1]); o.y = pk2(sum[2] * inv - uu[2], sum[3] * inv - uu[3]);
;     o.z = pk2(sum[4] * inv - uu[4], sum[5] * inv - uu[5]); o.w = pk2(sum[6] * inv - uu[6], sum[7] * inv - uu[7]);
;     *(u32x4*)(D + (size_t)r * 1024 + c0) = o;
	v_lshlrev_b32_e32 v206, 16, v76
	v_and_b32_e32 v207, 0xffff0000, v76
	v_lshlrev_b32_e32 v208, 16, v77
	v_and_b32_e32 v209, 0xffff0000, v77
	v_lshlrev_b32_e32 v210, 16, v78
	v_and_b32_e32 v211, 0xffff0000, v78
	v_lshlrev_b32_e32 v212, 16, v79
	v_and_b32_e32 v213, 0xffff0000, v79
	v_lshlrev_b32_e32 v214, 16, v80
	v_and_b32_e32 v215, 0xffff0000, v80
	v_lshlrev_b32_e32 v216, 16, v81
	v_and_b32_e32 v217, 0xffff0000, v81
	v_lshlrev_b32_e32 v218, 16, v82
	v_and_b32_e32 v219, 0xffff0000, v82
	v_lshlrev_b32_e32 v220, 16, v83
	v_and_b32_e32 v221, 0xffff0000, v83
	v_mov_b32_e32 v222, v206
	v_mov_b32_e32 v230, v214
	v_mov_b32_e32 v223, v207
	v_mov_b32_e32 v231, v215
	v_mov_b32_e32 v224, v208
	v_mov_b32_e32 v232, v216
	v_mov_b32_e32 v225, v209
	v_mov_b32_e32 v233, v217
	v_mov_b32_e32 v226, v210
	v_mov_b32_e32 v234, v218
	v_mov_b32_e32 v227, v211
	v_mov_b32_e32 v235, v219
	v_mov_b32_e32 v228, v212
	v_mov_b32_e32 v236, v220
	v_mov_b32_e32 v229, v213
	v_mov_b32_e32 v237, v221
	v_fmac_f32_e32 v222, v214, v34
	v_fmac_f32_e32 v223, v215, v34
	v_fmac_f32_e32 v224, v216, v34
	v_fmac_f32_e32 v225, v217, v34
	v_fmac_f32_e32 v226, v218, v34
	v_fmac_f32_e32 v227, v219, v34
	v_fmac_f32_e32 v228, v220, v34
	v_fmac_f32_e32 v229, v221, v34
	v_lshlrev_b32_e32 v238, 16, v84
	v_and_b32_e32 v239, 0xffff0000, v84
	v_lshlrev_b32_e32 v240, 16, v85
	v_and_b32_e32 v241, 0xffff0000, v85
	v_lshlrev_b32_e32 v242, 16, v86
	v_and_b32_e32 v243, 0xffff0000, v86
	v_lshlrev_b32_e32 v244, 16, v87
	v_and_b32_e32 v245, 0xffff0000, v87
	v_fmac_f32_e32 v222, v238, v35
	v_fmac_f32_e32 v230, v238, v35
	v_fmac_f32_e32 v223, v239, v35
	v_fmac_f32_e32 v231, v239, v35
	v_fmac_f32_e32 v224, v240, v35
	v_fmac_f32_e32 v232, v240, v35
	v_fmac_f32_e32 v225, v241, v35
	v_fmac_f32_e32 v233, v241, v35
	v_fmac_f32_e32 v226, v242, v35
	v_fmac_f32_e32 v234, v242, v35
	v_fmac_f32_e32 v227, v243, v35
	v_fmac_f32_e32 v235, v243, v35
	v_fmac_f32_e32 v228, v244, v35
	v_fmac_f32_e32 v236, v244, v35
	v_fmac_f32_e32 v229, v245, v35
	v_fmac_f32_e32 v237, v245, v35
	v_lshlrev_b32_e32 v238, 16, v88
	v_and_b32_e32 v239, 0xffff0000, v88
	v_lshlrev_b32_e32 v240, 16, v89
	v_and_b32_e32 v241, 0xffff0000, v89
	v_lshlrev_b32_e32 v242, 16, v90
	v_and_b32_e32 v243, 0xffff0000, v90
	v_lshlrev_b32_e32 v244, 16, v91
	v_and_b32_e32 v245, 0xffff0000, v91
	v_fmac_f32_e32 v222, v238, v36
	v_fmac_f32_e32 v230, v238, v36
	v_fmac_f32_e32 v223, v239, v36
	v_fmac_f32_e32 v231, v239, v36
	v_fmac_f32_e32 v224, v240, v36
	v_fmac_f32_e32 v232, v240, v36
	v_fmac_f32_e32 v225, v241, v36
	v_fmac_f32_e32 v233, v241, v36
	v_fmac_f32_e32 v226, v242, v36
	v_fmac_f32_e32 v234, v242, v36
	v_fmac_f32_e32 v227, v243, v36
	v_fmac_f32_e32 v235, v243, v36
	v_fmac_f32_e32 v228, v244, v36
	v_fmac_f32_e32 v236, v244, v36
	v_fmac_f32_e32 v229, v245, v36
	v_fmac_f32_e32 v237, v245, v36
	v_lshlrev_b32_e32 v238, 16, v92
	v_and_b32_e32 v239, 0xffff0000, v92
	v_lshlrev_b32_e32 v240, 16, v93
	v_and_b32_e32 v241, 0xffff0000, v93
	v_lshlrev_b32_e32 v242, 16, v94
	v_and_b32_e32 v243, 0xffff0000, v94
	v_lshlrev_b32_e32 v244, 16, v95
	v_and_b32_e32 v245, 0xffff0000, v95
	v_fmac_f32_e32 v230, v238, v37
	v_fmac_f32_e32 v231, v239, v37
	v_fmac_f32_e32 v232, v240, v37
	v_fmac_f32_e32 v233, v241, v37
	v_fmac_f32_e32 v234, v242, v37
	v_fmac_f32_e32 v235, v243, v37
	v_fmac_f32_e32 v236, v244, v37
	v_fmac_f32_e32 v237, v245, v37
	v_fma_f32 v222, v222, v51, -v206
	v_fma_f32 v230, v230, v55, -v214
	v_fma_f32 v223, v223, v51, -v207
	v_fma_f32 v231, v231, v55, -v215
	v_fma_f32 v224, v224, v51, -v208
	v_fma_f32 v232, v232, v55, -v216
	v_fma_f32 v225, v225, v51, -v209
	v_fma_f32 v233, v233, v55, -v217
	v_fma_f32 v226, v226, v51, -v210
	v_fma_f32 v234, v234, v55, -v218
	v_fma_f32 v227, v227, v51, -v211
	v_fma_f32 v235, v235, v55, -v219
	v_fma_f32 v228, v228, v51, -v212
	v_fma_f32 v236, v236, v55, -v220
	v_fma_f32 v229, v229, v51, -v213
	v_fma_f32 v237, v237, v55, -v221
	v_cvt_pk_bf16_f32 v246, v222, v223
	v_cvt_pk_bf16_f32 v247, v224, v225
	v_cvt_pk_bf16_f32 v248, v226, v227
	v_cvt_pk_bf16_f32 v249, v228, v229
	global_store_dwordx4 v7, v[246:249], s[84:85] offset:512
	s_nop 1
	v_cvt_pk_bf16_f32 v250, v230, v231
	v_cvt_pk_bf16_f32 v251, v232, v233
	v_cvt_pk_bf16_f32 v252, v234, v235
	v_cvt_pk_bf16_f32 v253, v236, v237
	global_store_dwordx4 v7, v[250:253], s[84:85] offset:-1536
	s_nop 1
	s_waitcnt vmcnt(21)
	v_lshlrev_b32_e32 v206, 16, v96
	v_and_b32_e32 v207, 0xffff0000, v96
	v_lshlrev_b32_e32 v208, 16, v97
	v_and_b32_e32 v209, 0xffff0000, v97
	v_lshlrev_b32_e32 v210, 16, v98
	v_and_b32_e32 v211, 0xffff0000, v98
	v_lshlrev_b32_e32 v212, 16, v99
	v_and_b32_e32 v213, 0xffff0000, v99
	v_lshlrev_b32_e32 v214, 16, v100
	v_and_b32_e32 v215, 0xffff0000, v100
	v_lshlrev_b32_e32 v216, 16, v101
	v_and_b32_e32 v217, 0xffff0000, v101
	v_lshlrev_b32_e32 v218, 16, v102
	v_and_b32_e32 v219, 0xffff0000, v102
	v_lshlrev_b32_e32 v220, 16, v103
	v_and_b32_e32 v221, 0xffff0000, v103
	v_mov_b32_e32 v222, v206
	v_mov_b32_e32 v230, v214
	v_mov_b32_e32 v223, v207
	v_mov_b32_e32 v231, v215
	v_mov_b32_e32 v224, v208
	v_mov_b32_e32 v232, v216
	v_mov_b32_e32 v225, v209
	v_mov_b32_e32 v233, v217
	v_mov_b32_e32 v226, v210
	v_mov_b32_e32 v234, v218
	v_mov_b32_e32 v227, v211
	v_mov_b32_e32 v235, v219
	v_mov_b32_e32 v228, v212
	v_mov_b32_e32 v236, v220
	v_mov_b32_e32 v229, v213
	v_mov_b32_e32 v237, v221
	v_fmac_f32_e32 v222, v214, v34
	v_fmac_f32_e32 v223, v215, v34
	v_fmac_f32_e32 v224, v216, v34
	v_fmac_f32_e32 v225, v217, v34
	v_fmac_f32_e32 v226, v218, v34
	v_fmac_f32_e32 v227, v219, v34
	v_fmac_f32_e32 v228, v220, v34
	v_fmac_f32_e32 v229, v221, v34
	v_lshlrev_b32_e32 v238, 16, v104
	v_and_b32_e32 v239, 0xffff0000, v104
	v_lshlrev_b32_e32 v240, 16, v105
	v_and_b32_e32 v241, 0xffff0000, v105
	v_lshlrev_b32_e32 v242, 16, v106
	v_and_b32_e32 v243, 0xffff0000, v106
	v_lshlrev_b32_e32 v244, 16, v107
	v_and_b32_e32 v245, 0xffff0000, v107
	v_fmac_f32_e32 v222, v238, v35
	v_fmac_f32_e32 v230, v238, v35
	v_fmac_f32_e32 v223, v239, v35
	v_fmac_f32_e32 v231, v239, v35
	v_fmac_f32_e32 v224, v240, v35
	v_fmac_f32_e32 v232, v240, v35
	v_fmac_f32_e32 v225, v241, v35
	v_fmac_f32_e32 v233, v241, v35
	v_fmac_f32_e32 v226, v242, v35
	v_fmac_f32_e32 v234, v242, v35
	v_fmac_f32_e32 v227, v243, v35
	v_fmac_f32_e32 v235, v243, v35
	v_fmac_f32_e32 v228, v244, v35
	v_fmac_f32_e32 v236, v244, v35
	v_fmac_f32_e32 v229, v245, v35
	v_fmac_f32_e32 v237, v245, v35
	v_lshlrev_b32_e32 v238, 16, v108
	v_and_b32_e32 v239, 0xffff0000, v108
	v_lshlrev_b32_e32 v240, 16, v109
	v_and_b32_e32 v241, 0xffff0000, v109
	v_lshlrev_b32_e32 v242, 16, v110
	v_and_b32_e32 v243, 0xffff0000, v110
	v_lshlrev_b32_e32 v244, 16, v111
	v_and_b32_e32 v245, 0xffff0000, v111
	v_fmac_f32_e32 v222, v238, v36
	v_fmac_f32_e32 v230, v238, v36
	v_fmac_f32_e32 v223, v239, v36
	v_fmac_f32_e32 v231, v239, v36
	v_fmac_f32_e32 v224, v240, v36
	v_fmac_f32_e32 v232, v240, v36
	v_fmac_f32_e32 v225, v241, v36
	v_fmac_f32_e32 v233, v241, v36
	v_fmac_f32_e32 v226, v242, v36
	v_fmac_f32_e32 v234, v242, v36
	v_fmac_f32_e32 v227, v243, v36
	v_fmac_f32_e32 v235, v243, v36
	v_fmac_f32_e32 v228, v244, v36
	v_fmac_f32_e32 v236, v244, v36
	v_fmac_f32_e32 v229, v245, v36
	v_fmac_f32_e32 v237, v245, v36
	v_lshlrev_b32_e32 v238, 16, v112
	v_and_b32_e32 v239, 0xffff0000, v112
	v_lshlrev_b32_e32 v240, 16, v113
	v_and_b32_e32 v241, 0xffff0000, v113
	v_lshlrev_b32_e32 v242, 16, v114
	v_and_b32_e32 v243, 0xffff0000, v114
	v_lshlrev_b32_e32 v244, 16, v115
	v_and_b32_e32 v245, 0xffff0000, v115
	v_fmac_f32_e32 v222, v238, v37
	v_fmac_f32_e32 v230, v238, v37
	v_fmac_f32_e32 v223, v239, v37
	v_fmac_f32_e32 v231, v239, v37
	v_fmac_f32_e32 v224, v240, v37
	v_fmac_f32_e32 v232, v240, v37
	v_fmac_f32_e32 v225, v241, v37
	v_fmac_f32_e32 v233, v241, v37
	v_fmac_f32_e32 v226, v242, v37
	v_fmac_f32_e32 v234, v242, v37
	v_fmac_f32_e32 v227, v243, v37
	v_fmac_f32_e32 v235, v243, v37
	v_fmac_f32_e32 v228, v244, v37
	v_fmac_f32_e32 v236, v244, v37
	v_fmac_f32_e32 v229, v245, v37
	v_fmac_f32_e32 v237, v245, v37
	v_lshlrev_b32_e32 v238, 16, v116
	v_and_b32_e32 v239, 0xffff0000, v116
	v_lshlrev_b32_e32 v240, 16, v117
	v_and_b32_e32 v241, 0xffff0000, v117
	v_lshlrev_b32_e32 v242, 16, v118
	v_and_b32_e32 v243, 0xffff0000, v118
	v_lshlrev_b32_e32 v244, 16, v119
	v_and_b32_e32 v245, 0xffff0000, v119
	v_fmac_f32_e32 v222, v238, v38
	v_fmac_f32_e32 v230, v238, v38
	v_fmac_f32_e32 v223, v239, v38
	v_fmac_f32_e32 v231, v239, v38
	v_fmac_f32_e32 v224, v240, v38
	v_fmac_f32_e32 v232, v240, v38
	v_fmac_f32_e32 v225, v241, v38
	v_fmac_f32_e32 v233, v241, v38
	v_fmac_f32_e32 v226, v242, v38
	v_fmac_f32_e32 v234, v242, v38
	v_fmac_f32_e32 v227, v243, v38
	v_fmac_f32_e32 v235, v243, v38
	v_fmac_f32_e32 v228, v244, v38
	v_fmac_f32_e32 v236, v244, v38
	v_fmac_f32_e32 v229, v245, v38
	v_fmac_f32_e32 v237, v245, v38
	v_lshlrev_b32_e32 v238, 16, v120
	v_and_b32_e32 v239, 0xffff0000, v120
	v_lshlrev_b32_e32 v240, 16, v121
	v_and_b32_e32 v241, 0xffff0000, v121
	v_lshlrev_b32_e32 v242, 16, v122
	v_and_b32_e32 v243, 0xffff0000, v122
	v_lshlrev_b32_e32 v244, 16, v123
	v_and_b32_e32 v245, 0xffff0000, v123
	v_fmac_f32_e32 v222, v238, v39
	v_fmac_f32_e32 v230, v238, v39
	v_fmac_f32_e32 v223, v239, v39
	v_fmac_f32_e32 v231, v239, v39
	v_fmac_f32_e32 v224, v240, v39
	v_fmac_f32_e32 v232, v240, v39
	v_fmac_f32_e32 v225, v241, v39
	v_fmac_f32_e32 v233, v241, v39
	v_fmac_f32_e32 v226, v242, v39
	v_fmac_f32_e32 v234, v242, v39
	v_fmac_f32_e32 v227, v243, v39
	v_fmac_f32_e32 v235, v243, v39
	v_fmac_f32_e32 v228, v244, v39
	v_fmac_f32_e32 v236, v244, v39
	v_fmac_f32_e32 v229, v245, v39
	v_fmac_f32_e32 v237, v245, v39
	v_lshlrev_b32_e32 v238, 16, v124
	v_and_b32_e32 v239, 0xffff0000, v124
	v_lshlrev_b32_e32 v240, 16, v125
	v_and_b32_e32 v241, 0xffff0000, v125
	v_lshlrev_b32_e32 v242, 16, v126
	v_and_b32_e32 v243, 0xffff0000, v126
	v_lshlrev_b32_e32 v244, 16, v127
	v_and_b32_e32 v245, 0xffff0000, v127
	v_fmac_f32_e32 v222, v238, v40
	v_fmac_f32_e32 v230, v238, v40
	v_fmac_f32_e32 v223, v239, v40
	v_fmac_f32_e32 v231, v239, v40
	v_fmac_f32_e32 v224, v240, v40
	v_fmac_f32_e32 v232, v240, v40
	v_fmac_f32_e32 v225, v241, v40
	v_fmac_f32_e32 v233, v241, v40
	v_fmac_f32_e32 v226, v242, v40
	v_fmac_f32_e32 v234, v242, v40
	v_fmac_f32_e32 v227, v243, v40
	v_fmac_f32_e32 v235, v243, v40
	v_fmac_f32_e32 v228, v244, v40
	v_fmac_f32_e32 v236, v244, v40
	v_fmac_f32_e32 v229, v245, v40
	v_fmac_f32_e32 v237, v245, v40
	v_lshlrev_b32_e32 v238, 16, v128
	v_and_b32_e32 v239, 0xffff0000, v128
	v_lshlrev_b32_e32 v240, 16, v129
	v_and_b32_e32 v241, 0xffff0000, v129
	v_lshlrev_b32_e32 v242, 16, v130
	v_and_b32_e32 v243, 0xffff0000, v130
	v_lshlrev_b32_e32 v244, 16, v131
	v_and_b32_e32 v245, 0xffff0000, v131
	v_fmac_f32_e32 v230, v238, v41
	v_fmac_f32_e32 v231, v239, v41
	v_fmac_f32_e32 v232, v240, v41
	v_fmac_f32_e32 v233, v241, v41
	v_fmac_f32_e32 v234, v242, v41
	v_fmac_f32_e32 v235, v243, v41
	v_fmac_f32_e32 v236, v244, v41
	v_fmac_f32_e32 v237, v245, v41
	v_fma_f32 v222, v222, v52, -v206
	v_fma_f32 v230, v230, v56, -v214
	v_fma_f32 v223, v223, v52, -v207
	v_fma_f32 v231, v231, v56, -v215
	v_fma_f32 v224, v224, v52, -v208
	v_fma_f32 v232, v232, v56, -v216
	v_fma_f32 v225, v225, v52, -v209
	v_fma_f32 v233, v233, v56, -v217
	v_fma_f32 v226, v226, v52, -v210
	v_fma_f32 v234, v234, v56, -v218
	v_fma_f32 v227, v227, v52, -v211
	v_fma_f32 v235, v235, v56, -v219
	v_fma_f32 v228, v228, v52, -v212
	v_fma_f32 v236, v236, v56, -v220
	v_fma_f32 v229, v229, v52, -v213
	v_fma_f32 v237, v237, v56, -v221
	v_cvt_pk_bf16_f32 v246, v222, v223
	v_cvt_pk_bf16_f32 v247, v224, v225
	v_cvt_pk_bf16_f32 v248, v226, v227
	v_cvt_pk_bf16_f32 v249, v228, v229
	global_store_dwordx4 v7, v[246:249], s[84:85] offset:1024
	s_nop 1
	v_cvt_pk_bf16_f32 v250, v230, v231
	v_cvt_pk_bf16_f32 v251, v232, v233
	v_cvt_pk_bf16_f32 v252, v234, v235
	v_cvt_pk_bf16_f32 v253, v236, v237
	global_store_dwordx4 v7, v[250:253], s[84:85] offset:-1024
	s_nop 1
	s_waitcnt vmcnt(6)
	v_lshlrev_b32_e32 v206, 16, v132
	v_and_b32_e32 v207, 0xffff0000, v132
	v_lshlrev_b32_e32 v208, 16, v133
	v_and_b32_e32 v209, 0xffff0000, v133
	v_lshlrev_b32_e32 v210, 16, v134
	v_and_b32_e32 v211, 0xffff0000, v134
	v_lshlrev_b32_e32 v212, 16, v135
	v_and_b32_e32 v213, 0xffff0000, v135
	v_lshlrev_b32_e32 v214, 16, v136
	v_and_b32_e32 v215, 0xffff0000, v136
	v_lshlrev_b32_e32 v216, 16, v137
	v_and_b32_e32 v217, 0xffff0000, v137
	v_lshlrev_b32_e32 v218, 16, v138
	v_and_b32_e32 v219, 0xffff0000, v138
	v_lshlrev_b32_e32 v220, 16, v139
	v_and_b32_e32 v221, 0xffff0000, v139
	v_mov_b32_e32 v222, v206
	v_mov_b32_e32 v230, v214
	v_mov_b32_e32 v223, v207
	v_mov_b32_e32 v231, v215
	v_mov_b32_e32 v224, v208
	v_mov_b32_e32 v232, v216
	v_mov_b32_e32 v225, v209
	v_mov_b32_e32 v233, v217
	v_mov_b32_e32 v226, v210
	v_mov_b32_e32 v234, v218
	v_mov_b32_e32 v227, v211
	v_mov_b32_e32 v235, v219
	v_mov_b32_e32 v228, v212
	v_mov_b32_e32 v236, v220
	v_mov_b32_e32 v229, v213
	v_mov_b32_e32 v237, v221
	v_fmac_f32_e32 v222, v214, v34
	v_fmac_f32_e32 v223, v215, v34
	v_fmac_f32_e32 v224, v216, v34
	v_fmac_f32_e32 v225, v217, v34
	v_fmac_f32_e32 v226, v218, v34
	v_fmac_f32_e32 v227, v219, v34
	v_fmac_f32_e32 v228, v220, v34
	v_fmac_f32_e32 v229, v221, v34
	v_lshlrev_b32_e32 v238, 16, v140
	v_and_b32_e32 v239, 0xffff0000, v140
	v_lshlrev_b32_e32 v240, 16, v141
	v_and_b32_e32 v241, 0xffff0000, v141
	v_lshlrev_b32_e32 v242, 16, v142
	v_and_b32_e32 v243, 0xffff0000, v142
	v_lshlrev_b32_e32 v244, 16, v143
	v_and_b32_e32 v245, 0xffff0000, v143
	v_fmac_f32_e32 v222, v238, v35
	v_fmac_f32_e32 v230, v238, v35
	v_fmac_f32_e32 v223, v239, v35
	v_fmac_f32_e32 v231, v239, v35
	v_fmac_f32_e32 v224, v240, v35
	v_fmac_f32_e32 v232, v240, v35
	v_fmac_f32_e32 v225, v241, v35
	v_fmac_f32_e32 v233, v241, v35
	v_fmac_f32_e32 v226, v242, v35
	v_fmac_f32_e32 v234, v242, v35
	v_fmac_f32_e32 v227, v243, v35
	v_fmac_f32_e32 v235, v243, v35
	v_fmac_f32_e32 v228, v244, v35
	v_fmac_f32_e32 v236, v244, v35
	v_fmac_f32_e32 v229, v245, v35
	v_fmac_f32_e32 v237, v245, v35
	v_lshlrev_b32_e32 v238, 16, v144
	v_and_b32_e32 v239, 0xffff0000, v144
	v_lshlrev_b32_e32 v240, 16, v145
	v_and_b32_e32 v241, 0xffff0000, v145
	v_lshlrev_b32_e32 v242, 16, v146
	v_and_b32_e32 v243, 0xffff0000, v146
	v_lshlrev_b32_e32 v244, 16, v147
	v_and_b32_e32 v245, 0xffff0000, v147
	v_fmac_f32_e32 v222, v238, v36
	v_fmac_f32_e32 v230, v238, v36
	v_fmac_f32_e32 v223, v239, v36
	v_fmac_f32_e32 v231, v239, v36
	v_fmac_f32_e32 v224, v240, v36
	v_fmac_f32_e32 v232, v240, v36
	v_fmac_f32_e32 v225, v241, v36
	v_fmac_f32_e32 v233, v241, v36
	v_fmac_f32_e32 v226, v242, v36
	v_fmac_f32_e32 v234, v242, v36
	v_fmac_f32_e32 v227, v243, v36
	v_fmac_f32_e32 v235, v243, v36
	v_fmac_f32_e32 v228, v244, v36
	v_fmac_f32_e32 v236, v244, v36
	v_fmac_f32_e32 v229, v245, v36
	v_fmac_f32_e32 v237, v245, v36
	v_lshlrev_b32_e32 v238, 16, v148
	v_and_b32_e32 v239, 0xffff0000, v148
	v_lshlrev_b32_e32 v240, 16, v149
	v_and_b32_e32 v241, 0xffff0000, v149
	v_lshlrev_b32_e32 v242, 16, v150
	v_and_b32_e32 v243, 0xffff0000, v150
	v_lshlrev_b32_e32 v244, 16, v151
	v_and_b32_e32 v245, 0xffff0000, v151
	v_fmac_f32_e32 v222, v238, v37
	v_fmac_f32_e32 v230, v238, v37
	v_fmac_f32_e32 v223, v239, v37
	v_fmac_f32_e32 v231, v239, v37
	v_fmac_f32_e32 v224, v240, v37
	v_fmac_f32_e32 v232, v240, v37
	v_fmac_f32_e32 v225, v241, v37
	v_fmac_f32_e32 v233, v241, v37
	v_fmac_f32_e32 v226, v242, v37
	v_fmac_f32_e32 v234, v242, v37
	v_fmac_f32_e32 v227, v243, v37
	v_fmac_f32_e32 v235, v243, v37
	v_fmac_f32_e32 v228, v244, v37
	v_fmac_f32_e32 v236, v244, v37
	v_fmac_f32_e32 v229, v245, v37
	v_fmac_f32_e32 v237, v245, v37
	v_lshlrev_b32_e32 v238, 16, v152
	v_and_b32_e32 v239, 0xffff0000, v152
	v_lshlrev_b32_e32 v240, 16, v153
	v_and_b32_e32 v241, 0xffff0000, v153
	v_lshlrev_b32_e32 v242, 16, v154
	v_and_b32_e32 v243, 0xffff0000, v154
	v_lshlrev_b32_e32 v244, 16, v155
	v_and_b32_e32 v245, 0xffff0000, v155
	v_fmac_f32_e32 v222, v238, v38
	v_fmac_f32_e32 v230, v238, v38
	v_fmac_f32_e32 v223, v239, v38
	v_fmac_f32_e32 v231, v239, v38
	v_fmac_f32_e32 v224, v240, v38
	v_fmac_f32_e32 v232, v240, v38
	v_fmac_f32_e32 v225, v241, v38
	v_fmac_f32_e32 v233, v241, v38
	v_fmac_f32_e32 v226, v242, v38
	v_fmac_f32_e32 v234, v242, v38
	v_fmac_f32_e32 v227, v243, v38
	v_fmac_f32_e32 v235, v243, v38
	v_fmac_f32_e32 v228, v244, v38
	v_fmac_f32_e32 v236, v244, v38
	v_fmac_f32_e32 v229, v245, v38
	v_fmac_f32_e32 v237, v245, v38
	v_lshlrev_b32_e32 v238, 16, v156
	v_and_b32_e32 v239, 0xffff0000, v156
	v_lshlrev_b32_e32 v240, 16, v157
	v_and_b32_e32 v241, 0xffff0000, v157
	v_lshlrev_b32_e32 v242, 16, v158
	v_and_b32_e32 v243, 0xffff0000, v158
	v_lshlrev_b32_e32 v244, 16, v159
	v_and_b32_e32 v245, 0xffff0000, v159
	v_fmac_f32_e32 v222, v238, v39
	v_fmac_f32_e32 v230, v238, v39
	v_fmac_f32_e32 v223, v239, v39
	v_fmac_f32_e32 v231, v239, v39
	v_fmac_f32_e32 v224, v240, v39
	v_fmac_f32_e32 v232, v240, v39
	v_fmac_f32_e32 v225, v241, v39
	v_fmac_f32_e32 v233, v241, v39
	v_fmac_f32_e32 v226, v242, v39
	v_fmac_f32_e32 v234, v242, v39
	v_fmac_f32_e32 v227, v243, v39
	v_fmac_f32_e32 v235, v243, v39
	v_fmac_f32_e32 v228, v244, v39
	v_fmac_f32_e32 v236, v244, v39
	v_fmac_f32_e32 v229, v245, v39
	v_fmac_f32_e32 v237, v245, v39
	v_lshlrev_b32_e32 v238, 16, v160
	v_and_b32_e32 v239, 0xffff0000, v160
	v_lshlrev_b32_e32 v240, 16, v161
	v_and_b32_e32 v241, 0xffff0000, v161
	v_lshlrev_b32_e32 v242, 16, v162
	v_and_b32_e32 v243, 0xffff0000, v162
	v_lshlrev_b32_e32 v244, 16, v163
	v_and_b32_e32 v245, 0xffff0000, v163
	v_fmac_f32_e32 v222, v238, v40
	v_fmac_f32_e32 v230, v238, v40
	v_fmac_f32_e32 v223, v239, v40
	v_fmac_f32_e32 v231, v239, v40
	v_fmac_f32_e32 v224, v240, v40
	v_fmac_f32_e32 v232, v240, v40
	v_fmac_f32_e32 v225, v241, v40
	v_fmac_f32_e32 v233, v241, v40
	v_fmac_f32_e32 v226, v242, v40
	v_fmac_f32_e32 v234, v242, v40
	v_fmac_f32_e32 v227, v243, v40
	v_fmac_f32_e32 v235, v243, v40
	v_fmac_f32_e32 v228, v244, v40
	v_fmac_f32_e32 v236, v244, v40
	v_fmac_f32_e32 v229, v245, v40
	v_fmac_f32_e32 v237, v245, v40
	v_lshlrev_b32_e32 v238, 16, v164
	v_and_b32_e32 v239, 0xffff0000, v164
	v_lshlrev_b32_e32 v240, 16, v165
	v_and_b32_e32 v241, 0xffff0000, v165
	v_lshlrev_b32_e32 v242, 16, v166
	v_and_b32_e32 v243, 0xffff0000, v166
	v_lshlrev_b32_e32 v244, 16, v167
	v_and_b32_e32 v245, 0xffff0000, v167
	v_fmac_f32_e32 v222, v238, v41
	v_fmac_f32_e32 v230, v238, v41
	v_fmac_f32_e32 v223, v239, v41
	v_fmac_f32_e32 v231, v239, v41
	v_fmac_f32_e32 v224, v240, v41
	v_fmac_f32_e32 v232, v240, v41
	v_fmac_f32_e32 v225, v241, v41
	v_fmac_f32_e32 v233, v241, v41
	v_fmac_f32_e32 v226, v242, v41
	v_fmac_f32_e32 v234, v242, v41
	v_fmac_f32_e32 v227, v243, v41
	v_fmac_f32_e32 v235, v243, v41
	v_fmac_f32_e32 v228, v244, v41
	v_fmac_f32_e32 v236, v244, v41
	v_fmac_f32_e32 v229, v245, v41
	v_fmac_f32_e32 v237, v245, v41
	v_lshlrev_b32_e32 v238, 16, v168
	v_and_b32_e32 v239, 0xffff0000, v168
	v_lshlrev_b32_e32 v240, 16, v169
	v_and_b32_e32 v241, 0xffff0000, v169
	v_lshlrev_b32_e32 v242, 16, v170
	v_and_b32_e32 v243, 0xffff0000, v170
	v_lshlrev_b32_e32 v244, 16, v171
	v_and_b32_e32 v245, 0xffff0000, v171
	v_fmac_f32_e32 v222, v238, v42
	v_fmac_f32_e32 v230, v238, v42
	v_fmac_f32_e32 v223, v239, v42
	v_fmac_f32_e32 v231, v239, v42
	v_fmac_f32_e32 v224, v240, v42
	v_fmac_f32_e32 v232, v240, v42
	v_fmac_f32_e32 v225, v241, v42
	v_fmac_f32_e32 v233, v241, v42
	v_fmac_f32_e32 v226, v242, v42
	v_fmac_f32_e32 v234, v242, v42
	v_fmac_f32_e32 v227, v243, v42
	v_fmac_f32_e32 v235, v243, v42
	v_fmac_f32_e32 v228, v244, v42
	v_fmac_f32_e32 v236, v244, v42
	v_fmac_f32_e32 v229, v245, v42
	v_fmac_f32_e32 v237, v245, v42
	v_lshlrev_b32_e32 v238, 16, v172
	v_and_b32_e32 v239, 0xffff0000, v172
	v_lshlrev_b32_e32 v240, 16, v173
	v_and_b32_e32 v241, 0xffff0000, v173
	v_lshlrev_b32_e32 v242, 16, v174
	v_and_b32_e32 v243, 0xffff0000, v174
	v_lshlrev_b32_e32 v244, 16, v175
	v_and_b32_e32 v245, 0xffff0000, v175
	v_fmac_f32_e32 v222, v238, v43
	v_fmac_f32_e32 v230, v238, v43
	v_fmac_f32_e32 v223, v239, v43
	v_fmac_f32_e32 v231, v239, v43
	v_fmac_f32_e32 v224, v240, v43
	v_fmac_f32_e32 v232, v240, v43
	v_fmac_f32_e32 v225, v241, v43
	v_fmac_f32_e32 v233, v241, v43
	v_fmac_f32_e32 v226, v242, v43
	v_fmac_f32_e32 v234, v242, v43
	v_fmac_f32_e32 v227, v243, v43
	v_fmac_f32_e32 v235, v243, v43
	v_fmac_f32_e32 v228, v244, v43
	v_fmac_f32_e32 v236, v244, v43
	v_fmac_f32_e32 v229, v245, v43
	v_fmac_f32_e32 v237, v245, v43
	v_lshlrev_b32_e32 v238, 16, v176
	v_and_b32_e32 v239, 0xffff0000, v176
	v_lshlrev_b32_e32 v240, 16, v177
	v_and_b32_e32 v241, 0xffff0000, v177
	v_lshlrev_b32_e32 v242, 16, v178
	v_and_b32_e32 v243, 0xffff0000, v178
	v_lshlrev_b32_e32 v244, 16, v179
	v_and_b32_e32 v245, 0xffff0000, v179
	v_fmac_f32_e32 v222, v238, v44
	v_fmac_f32_e32 v230, v238, v44
	v_fmac_f32_e32 v223, v239, v44
	v_fmac_f32_e32 v231, v239, v44
	v_fmac_f32_e32 v224, v240, v44
	v_fmac_f32_e32 v232, v240, v44
	v_fmac_f32_e32 v225, v241, v44
	v_fmac_f32_e32 v233, v241, v44
	v_fmac_f32_e32 v226, v242, v44
	v_fmac_f32_e32 v234, v242, v44
	v_fmac_f32_e32 v227, v243, v44
	v_fmac_f32_e32 v235, v243, v44
	v_fmac_f32_e32 v228, v244, v44
	v_fmac_f32_e32 v236, v244, v44
	v_fmac_f32_e32 v229, v245, v44
	v_fmac_f32_e32 v237, v245, v44
	v_lshlrev_b32_e32 v238, 16, v180
	v_and_b32_e32 v239, 0xffff0000, v180
	v_lshlrev_b32_e32 v240, 16, v181
	v_and_b32_e32 v241, 0xffff0000, v181
	v_lshlrev_b32_e32 v242, 16, v182
	v_and_b32_e32 v243, 0xffff0000, v182
	v_lshlrev_b32_e32 v244, 16, v183
	v_and_b32_e32 v245, 0xffff0000, v183
	v_fmac_f32_e32 v222, v238, v45
	v_fmac_f32_e32 v230, v238, v45
	v_fmac_f32_e32 v223, v239, v45
	v_fmac_f32_e32 v231, v239, v45
	v_fmac_f32_e32 v224, v240, v45
	v_fmac_f32_e32 v232, v240, v45
	v_fmac_f32_e32 v225, v241, v45
	v_fmac_f32_e32 v233, v241, v45
	v_fmac_f32_e32 v226, v242, v45
	v_fmac_f32_e32 v234, v242, v45
	v_fmac_f32_e32 v227, v243, v45
	v_fmac_f32_e32 v235, v243, v45
	v_fmac_f32_e32 v228, v244, v45
	v_fmac_f32_e32 v236, v244, v45
	v_fmac_f32_e32 v229, v245, v45
	v_fmac_f32_e32 v237, v245, v45
	v_lshlrev_b32_e32 v238, 16, v184
	v_and_b32_e32 v239, 0xffff0000, v184
	v_lshlrev_b32_e32 v240, 16, v185
	v_and_b32_e32 v241, 0xffff0000, v185
	v_lshlrev_b32_e32 v242, 16, v186
	v_and_b32_e32 v243, 0xffff0000, v186
	v_lshlrev_b32_e32 v244, 16, v187
	v_and_b32_e32 v245, 0xffff0000, v187
	v_fmac_f32_e32 v222, v238, v46
	v_fmac_f32_e32 v230, v238, v46
	v_fmac_f32_e32 v223, v239, v46
	v_fmac_f32_e32 v231, v239, v46
	v_fmac_f32_e32 v224, v240, v46
	v_fmac_f32_e32 v232, v240, v46
	v_fmac_f32_e32 v225, v241, v46
	v_fmac_f32_e32 v233, v241, v46
	v_fmac_f32_e32 v226, v242, v46
	v_fmac_f32_e32 v234, v242, v46
	v_fmac_f32_e32 v227, v243, v46
	v_fmac_f32_e32 v235, v243, v46
	v_fmac_f32_e32 v228, v244, v46
	v_fmac_f32_e32 v236, v244, v46
	v_fmac_f32_e32 v229, v245, v46
	v_fmac_f32_e32 v237, v245, v46
	v_lshlrev_b32_e32 v238, 16, v188
	v_and_b32_e32 v239, 0xffff0000, v188
	v_lshlrev_b32_e32 v240, 16, v189
	v_and_b32_e32 v241, 0xffff0000, v189
	v_lshlrev_b32_e32 v242, 16, v190
	v_and_b32_e32 v243, 0xffff0000, v190
	v_lshlrev_b32_e32 v244, 16, v191
	v_and_b32_e32 v245, 0xffff0000, v191
	v_fmac_f32_e32 v222, v238, v47
	v_fmac_f32_e32 v230, v238, v47
	v_fmac_f32_e32 v223, v239, v47
	v_fmac_f32_e32 v231, v239, v47
	v_fmac_f32_e32 v224, v240, v47
	v_fmac_f32_e32 v232, v240, v47
	v_fmac_f32_e32 v225, v241, v47
	v_fmac_f32_e32 v233, v241, v47
	v_fmac_f32_e32 v226, v242, v47
	v_fmac_f32_e32 v234, v242, v47
	v_fmac_f32_e32 v227, v243, v47
	v_fmac_f32_e32 v235, v243, v47
	v_fmac_f32_e32 v228, v244, v47
	v_fmac_f32_e32 v236, v244, v47
	v_fmac_f32_e32 v229, v245, v47
	v_fmac_f32_e32 v237, v245, v47
	v_lshlrev_b32_e32 v238, 16, v192
	v_and_b32_e32 v239, 0xffff0000, v192
	v_lshlrev_b32_e32 v240, 16, v193
	v_and_b32_e32 v241, 0xffff0000, v193
	v_lshlrev_b32_e32 v242, 16, v194
	v_and_b32_e32 v243, 0xffff0000, v194
	v_lshlrev_b32_e32 v244, 16, v195
	v_and_b32_e32 v245, 0xffff0000, v195
	v_fmac_f32_e32 v222, v238, v48
	v_fmac_f32_e32 v230, v238, v48
	v_fmac_f32_e32 v223, v239, v48
	v_fmac_f32_e32 v231, v239, v48
	v_fmac_f32_e32 v224, v240, v48
	v_fmac_f32_e32 v232, v240, v48
	v_fmac_f32_e32 v225, v241, v48
	v_fmac_f32_e32 v233, v241, v48
	v_fmac_f32_e32 v226, v242, v48
	v_fmac_f32_e32 v234, v242, v48
	v_fmac_f32_e32 v227, v243, v48
	v_fmac_f32_e32 v235, v243, v48
	v_fmac_f32_e32 v228, v244, v48
	v_fmac_f32_e32 v236, v244, v48
	v_fmac_f32_e32 v229, v245, v48
	v_fmac_f32_e32 v237, v245, v48
	v_lshlrev_b32_e32 v238, 16, v196
	v_and_b32_e32 v239, 0xffff0000, v196
	v_lshlrev_b32_e32 v240, 16, v197
	v_and_b32_e32 v241, 0xffff0000, v197
	v_lshlrev_b32_e32 v242, 16, v198
	v_and_b32_e32 v243, 0xffff0000, v198
	v_lshlrev_b32_e32 v244, 16, v199
	v_and_b32_e32 v245, 0xffff0000, v199
	v_fmac_f32_e32 v230, v238, v49
	v_fmac_f32_e32 v231, v239, v49
	v_fmac_f32_e32 v232, v240, v49
	v_fmac_f32_e32 v233, v241, v49
	v_fmac_f32_e32 v234, v242, v49
	v_fmac_f32_e32 v235, v243, v49
	v_fmac_f32_e32 v236, v244, v49
	v_fmac_f32_e32 v237, v245, v49
	v_fma_f32 v222, v222, v53, -v206
	v_fma_f32 v230, v230, v57, -v214
	v_fma_f32 v223, v223, v53, -v207
	v_fma_f32 v231, v231, v57, -v215
	v_fma_f32 v224, v224, v53, -v208
	v_fma_f32 v232, v232, v57, -v216
	v_fma_f32 v225, v225, v53, -v209
	v_fma_f32 v233, v233, v57, -v217
	v_fma_f32 v226, v226, v53, -v210
	v_fma_f32 v234, v234, v57, -v218
	v_fma_f32 v227, v227, v53, -v211
	v_fma_f32 v235, v235, v57, -v219
	v_fma_f32 v228, v228, v53, -v212
	v_fma_f32 v236, v236, v57, -v220
	v_fma_f32 v229, v229, v53, -v213
	v_fma_f32 v237, v237, v57, -v221
	v_cvt_pk_bf16_f32 v246, v222, v223
	v_cvt_pk_bf16_f32 v247, v224, v225
	v_cvt_pk_bf16_f32 v248, v226, v227
	v_cvt_pk_bf16_f32 v249, v228, v229
	global_store_dwordx4 v7, v[246:249], s[84:85] offset:1536
	s_nop 1
	v_cvt_pk_bf16_f32 v250, v230, v231
	v_cvt_pk_bf16_f32 v251, v232, v233
	v_cvt_pk_bf16_f32 v252, v234, v235
	v_cvt_pk_bf16_f32 v253, v236, v237
	global_store_dwordx4 v7, v[250:253], s[84:85] offset:-512
	s_nop 1
	v_add_u32_e32 v2, 0x40000, v2
	s_cmp_gt_u32 s2, 31
	s_cbranch_scc1 .Lpoold_done
	s_lshr_b32 s90, s2, 3
	s_lshl_b32 s91, s90, 12
	v_subrev_u32_e32 v2, s91, v2
	v_lshrrev_b32_e32 v3, 5, v2
	v_and_b32_e32 v5, 31, v2
	v_lshlrev_b32_e32 v5, 4, v5
	v_mul_u32_u24_e32 v6, 0x4800, v3
	v_add_u32_e32 v6, v6, v5
	v_lshl_add_u32 v7, v3, 11, v5
	v_add_u32_e32 v8, 0xffffe000, v3
	v_mul_u32_u24_e32 v8, 0xf000, v8
	v_lshl_add_u32 v8, v5, 1, v8
	s_cmp_lg_u32 s90, 0
	s_cbranch_scc1 .Lpoold_sg0_end
	global_load_dwordx4 v[64:67], v6, s[28:29]
	s_add_u32 s88, s60, 0xe000
	s_addc_u32 s89, s61, 0
	global_load_dwordx4 v[68:71], v8, s[88:89]
	global_load_dwordx4 v[72:75], v8, s[88:89] offset:16
	s_waitcnt vmcnt(0)
	v_lshlrev_b32_e32 v220, 16, v64
	v_and_b32_e32 v221, 0xffff0000, v64
	v_lshlrev_b32_e32 v222, 16, v65
	v_and_b32_e32 v223, 0xffff0000, v65
	v_lshlrev_b32_e32 v224, 16, v66
	v_and_b32_e32 v225, 0xffff0000, v66
	v_lshlrev_b32_e32 v226, 16, v67
	v_and_b32_e32 v227, 0xffff0000, v67
	v_mov_b32_e32 v228, v220
	v_mov_b32_e32 v229, v221
	v_mov_b32_e32 v230, v222
	v_mov_b32_e32 v231, v223
	v_mov_b32_e32 v232, v224
	v_mov_b32_e32 v233, v225
	v_mov_b32_e32 v234, v226
	v_mov_b32_e32 v235, v227
	v_add_f32_e32 v228, v228, v68
	v_add_f32_e32 v229, v229, v69
	v_add_f32_e32 v230, v230, v70
	v_add_f32_e32 v231, v231, v71
	v_add_f32_e32 v232, v232, v72
	v_add_f32_e32 v233, v233, v73
	v_add_f32_e32 v234, v234, v74
	v_add_f32_e32 v235, v235, v75
	v_mov_b32_e32 v48, 0x3f000000
	v_fma_f32 v228, v228, v48, -v220
	v_fma_f32 v229, v229, v48, -v221
	v_fma_f32 v230, v230, v48, -v222
	v_fma_f32 v231, v231, v48, -v223
	v_fma_f32 v232, v232, v48, -v224
	v_fma_f32 v233, v233, v48, -v225
	v_fma_f32 v234, v234, v48, -v226
	v_fma_f32 v235, v235, v48, -v227
	v_cvt_pk_bf16_f32 v244, v228, v229
	v_cvt_pk_bf16_f32 v245, v230, v231
	v_cvt_pk_bf16_f32 v246, v232, v233
	v_cvt_pk_bf16_f32 v247, v234, v235
	global_store_dwordx4 v7, v[244:247], s[84:85]
	s_nop 1
.Lpoold_sg0_end:
	s_cmp_lg_u32 s90, 1
	s_cbranch_scc1 .Lpoold_sg1_end
	global_load_dwordx4 v[64:67], v6, s[28:29] offset:512
	s_add_u32 s88, s60, 0xe400
	s_addc_u32 s89, s61, 0
	global_load_dwordx4 v[68:71], v8, s[88:89]
	global_load_dwordx4 v[72:75], v8, s[88:89] offset:16
	s_add_u32 s88, s60, 0xd400
	s_addc_u32 s89, s61, 0
	global_load_dwordx4 v[76:79], v8, s[88:89]
	global_load_dwordx4 v[80:83], v8, s[88:89] offset:16
	s_add_u32 s88, s60, 0xc400
	s_addc_u32 s89, s61, 0
	global_load_dwordx4 v[84:87], v8, s[88:89]
	global_load_dwordx4 v[88:91], v8, s[88:89] offset:16
	s_waitcnt vmcnt(0)
	v_lshlrev_b32_e32 v220, 16, v64
	v_and_b32_e32 v221, 0xffff0000, v64
	v_lshlrev_b32_e32 v222, 16, v65
	v_and_b32_e32 v223, 0xffff0000, v65
	v_lshlrev_b32_e32 v224, 16, v66
	v_and_b32_e32 v225, 0xffff0000, v66
	v_lshlrev_b32_e32 v226, 16, v67
	v_and_b32_e32 v227, 0xffff0000, v67
	v_mov_b32_e32 v228, v220
	v_mov_b32_e32 v229, v221
	v_mov_b32_e32 v230, v222
	v_mov_b32_e32 v231, v223
	v_mov_b32_e32 v232, v224
	v_mov_b32_e32 v233, v225
	v_mov_b32_e32 v234, v226
	v_mov_b32_e32 v235, v227
	v_add_f32_e32 v228, v228, v68
	v_add_f32_e32 v229, v229, v69
	v_add_f32_e32 v230, v230, v70
	v_add_f32_e32 v231, v231, v71
	v_add_f32_e32 v232, v232, v72
	v_add_f32_e32 v233, v233, v73
	v_add_f32_e32 v234, v234, v74
	v_add_f32_e32 v235, v235, v75
	v_add_f32_e32 v228, v228, v76
	v_add_f32_e32 v229, v229, v77
	v_add_f32_e32 v230, v230, v78
	v_add_f32_e32 v231, v231, v79
	v_add_f32_e32 v232, v232, v80
	v_add_f32_e32 v233, v233, v81
	v_add_f32_e32 v234, v234, v82
	v_add_f32_e32 v235, v235, v83
	v_add_f32_e32 v228, v228, v84
	v_add_f32_e32 v229, v229, v85
	v_add_f32_e32 v230, v230, v86
	v_add_f32_e32 v231, v231, v87
	v_add_f32_e32 v232, v232, v88
	v_add_f32_e32 v233, v233, v89
	v_add_f32_e32 v234, v234, v90
	v_add_f32_e32 v235, v235, v91
	v_mov_b32_e32 v48, 0x3e800000
	v_fma_f32 v228, v228, v48, -v220
	v_fma_f32 v229, v229, v48, -v221
	v_fma_f32 v230, v230, v48, -v222
	v_fma_f32 v231, v231, v48, -v223
	v_fma_f32 v232, v232, v48, -v224
	v_fma_f32 v233, v233, v48, -v225
	v_fma_f32 v234, v234, v48, -v226
	v_fma_f32 v235, v235, v48, -v227
	v_cvt_pk_bf16_f32 v244, v228, v229
	v_cvt_pk_bf16_f32 v245, v230, v231
	v_cvt_pk_bf16_f32 v246, v232, v233
	v_cvt_pk_bf16_f32 v247, v234, v235
	global_store_dwordx4 v7, v[244:247], s[84:85] offset:512
	s_nop 1
.Lpoold_sg1_end:
	s_cmp_lg_u32 s90, 2
	s_cbranch_scc1 .Lpoold_sg2_end
	global_load_dwordx4 v[64:67], v6, s[28:29] offset:1024
	s_add_u32 s88, s60, 0xe800
	s_addc_u32 s89, s61, 0
	global_load_dwordx4 v[68:71], v8, s[88:89]
	global_load_dwordx4 v[72:75], v8, s[88:89] offset:16
	s_add_u32 s88, s60, 0xd800
	s_addc_u32 s89, s61, 0
	global_load_dwordx4 v[76:79], v8, s[88:89]
	global_load_dwordx4 v[80:83], v8, s[88:89] offset:16
	s_add_u32 s88, s60, 0xc800
	s_addc_u32 s89, s61, 0
	global_load_dwordx4 v[84:87], v8, s[88:89]
	global_load_dwordx4 v[88:91], v8, s[88:89] offset:16
	s_add_u32 s88, s60, 0xb800
	s_addc_u32 s89, s61, 0
	global_load_dwordx4 v[92:95], v8, s[88:89]
	global_load_dwordx4 v[96:99], v8, s[88:89] offset:16
	s_add_u32 s88, s60, 0xa800
	s_addc_u32 s89, s61, 0
	global_load_dwordx4 v[100:103], v8, s[88:89]
	global_load_dwordx4 v[104:107], v8, s[88:89] offset:16
	s_add_u32 s88, s60, 0x9800
	s_addc_u32 s89, s61, 0
	global_load_dwordx4 v[108:111], v8, s[88:89]
	global_load_dwordx4 v[112:115], v8, s[88:89] offset:16
	s_add_u32 s88, s60, 0x8800
	s_addc_u32 s89, s61, 0
	global_load_dwordx4 v[116:119], v8, s[88:89]
	global_load_dwordx4 v[120:123], v8, s[88:89] offset:16
	s_waitcnt vmcnt(0)
	v_lshlrev_b32_e32 v220, 16, v64
	v_and_b32_e32 v221, 0xffff0000, v64
	v_lshlrev_b32_e32 v222, 16, v65
	v_and_b32_e32 v223, 0xffff0000, v65
	v_lshlrev_b32_e32 v224, 16, v66
	v_and_b32_e32 v225, 0xffff0000, v66
	v_lshlrev_b32_e32 v226, 16, v67
	v_and_b32_e32 v227, 0xffff0000, v67
	v_mov_b32_e32 v228, v220
	v_mov_b32_e32 v229, v221
	v_mov_b32_e32 v230, v222
	v_mov_b32_e32 v231, v223
	v_mov_b32_e32 v232, v224
	v_mov_b32_e32 v233, v225
	v_mov_b32_e32 v234, v226
	v_mov_b32_e32 v235, v227
	v_add_f32_e32 v228, v228, v68
	v_add_f32_e32 v229, v229, v69
	v_add_f32_e32 v230, v230, v70
	v_add_f32_e32 v231, v231, v71
	v_add_f32_e32 v232, v232, v72
	v_add_f32_e32 v233, v233, v73
	v_add_f32_e32 v234, v234, v74
	v_add_f32_e32 v235, v235, v75
	v_add_f32_e32 v228, v228, v76
	v_add_f32_e32 v229, v229, v77
	v_add_f32_e32 v230, v230, v78
	v_add_f32_e32 v231, v231, v79
	v_add_f32_e32 v232, v232, v80
	v_add_f32_e32 v233, v233, v81
	v_add_f32_e32 v234, v234, v82
	v_add_f32_e32 v235, v235, v83
	v_add_f32_e32 v228, v228, v84
	v_add_f32_e32 v229, v229, v85
	v_add_f32_e32 v230, v230, v86
	v_add_f32_e32 v231, v231, v87
	v_add_f32_e32 v232, v232, v88
	v_add_f32_e32 v233, v233, v89
	v_add_f32_e32 v234, v234, v90
	v_add_f32_e32 v235, v235, v91
	v_add_f32_e32 v228, v228, v92
	v_add_f32_e32 v229, v229, v93
	v_add_f32_e32 v230, v230, v94
	v_add_f32_e32 v231, v231, v95
	v_add_f32_e32 v232, v232, v96
	v_add_f32_e32 v233, v233, v97
	v_add_f32_e32 v234, v234, v98
	v_add_f32_e32 v235, v235, v99
	v_add_f32_e32 v228, v228, v100
	v_add_f32_e32 v229, v229, v101
	v_add_f32_e32 v230, v230, v102
	v_add_f32_e32 v231, v231, v103
	v_add_f32_e32 v232, v232, v104
	v_add_f32_e32 v233, v233, v105
	v_add_f32_e32 v234, v234, v106
	v_add_f32_e32 v235, v235, v107
	v_add_f32_e32 v228, v228, v108
	v_add_f32_e32 v229, v229, v109
	v_add_f32_e32 v230, v230, v110
	v_add_f32_e32 v231, v231, v111
	v_add_f32_e32 v232, v232, v112
	v_add_f32_e32 v233, v233, v113
	v_add_f32_e32 v234, v234, v114
	v_add_f32_e32 v235, v235, v115
	v_add_f32_e32 v228, v228, v116
	v_add_f32_e32 v229, v229, v117
	v_add_f32_e32 v230, v230, v118
	v_add_f32_e32 v231, v231, v119
	v_add_f32_e32 v232, v232, v120
	v_add_f32_e32 v233, v233, v121
	v_add_f32_e32 v234, v234, v122
	v_add_f32_e32 v235, v235, v123
	v_mov_b32_e32 v48, 0x3e000000
	v_fma_f32 v228, v228, v48, -v220
	v_fma_f32 v229, v229, v48, -v221
	v_fma_f32 v230, v230, v48, -v222
	v_fma_f32 v231, v231, v48, -v223
	v_fma_f32 v232, v232, v48, -v224
	v_fma_f32 v233, v233, v48, -v225
	v_fma_f32 v234, v234, v48, -v226
	v_fma_f32 v235, v235, v48, -v227
	v_cvt_pk_bf16_f32 v244, v228, v229
	v_cvt_pk_bf16_f32 v245, v230, v231
	v_cvt_pk_bf16_f32 v246, v232, v233
	v_cvt_pk_bf16_f32 v247, v234, v235
	global_store_dwordx4 v7, v[244:247], s[84:85] offset:1024
	s_nop 1
.Lpoold_sg2_end:
	s_cmp_lg_u32 s90, 3
	s_cbranch_scc1 .Lpoold_sg3_end
	global_load_dwordx4 v[64:67], v6, s[28:29] offset:1536
	s_add_u32 s88, s60, 0xec00
	s_addc_u32 s89, s61, 0
	global_load_dwordx4 v[68:71], v8, s[88:89]
	global_load_dwordx4 v[72:75], v8, s[88:89] offset:16
	s_add_u32 s88, s60, 0xdc00
	s_addc_u32 s89, s61, 0
	global_load_dwordx4 v[76:79], v8, s[88:89]
	global_load_dwordx4 v[80:83], v8, s[88:89] offset:16
	s_add_u32 s88, s60, 0xcc00
	s_addc_u32 s89, s61, 0
	global_load_dwordx4 v[84:87], v8, s[88:89]
	global_load_dwordx4 v[88:91], v8, s[88:89] offset:16
	s_add_u32 s88, s60, 0xbc00
	s_addc_u32 s89, s61, 0
	global_load_dwordx4 v[92:95], v8, s[88:89]
	global_load_dwordx4 v[96:99], v8, s[88:89] offset:16
	s_add_u32 s88, s60, 0xac00
	s_addc_u32 s89, s61, 0
	global_load_dwordx4 v[100:103], v8, s[88:89]
	global_load_dwordx4 v[104:107], v8, s[88:89] offset:16
	s_add_u32 s88, s60, 0x9c00
	s_addc_u32 s89, s61, 0
	global_load_dwordx4 v[108:111], v8, s[88:89]
	global_load_dwordx4 v[112:115], v8, s[88:89] offset:16
	s_add_u32 s88, s60, 0x8c00
	s_addc_u32 s89, s61, 0
	global_load_dwordx4 v[116:119], v8, s[88:89]
	global_load_dwordx4 v[120:123], v8, s[88:89] offset:16
	s_add_u32 s88, s60, 0x7c00
	s_addc_u32 s89, s61, 0
	global_load_dwordx4 v[124:127], v8, s[88:89]
	global_load_dwordx4 v[128:131], v8, s[88:89] offset:16
	s_add_u32 s88, s60, 0x6c00
	s_addc_u32 s89, s61, 0
	global_load_dwordx4 v[132:135], v8, s[88:89]
	global_load_dwordx4 v[136:139], v8, s[88:89] offset:16
	s_add_u32 s88, s60, 0x5c00
	s_addc_u32 s89, s61, 0
	global_load_dwordx4 v[140:143], v8, s[88:89]
	global_load_dwordx4 v[144:147], v8, s[88:89] offset:16
	s_add_u32 s88, s60, 0x4c00
	s_addc_u32 s89, s61, 0
	global_load_dwordx4 v[148:151], v8, s[88:89]
	global_load_dwordx4 v[152:155], v8, s[88:89] offset:16
	s_add_u32 s88, s60, 0x3c00
	s_addc_u32 s89, s61, 0
	global_load_dwordx4 v[156:159], v8, s[88:89]
	global_load_dwordx4 v[160:163], v8, s[88:89] offset:16
	s_add_u32 s88, s60, 0x2c00
	s_addc_u32 s89, s61, 0
	global_load_dwordx4 v[164:167], v8, s[88:89]
	global_load_dwordx4 v[168:171], v8, s[88:89] offset:16
	s_add_u32 s88, s60, 0x1c00
	s_addc_u32 s89, s61, 0
	global_load_dwordx4 v[172:175], v8, s[88:89]
	global_load_dwordx4 v[176:179], v8, s[88:89] offset:16
	s_add_u32 s88, s60, 0xc00
	s_addc_u32 s89, s61, 0
	global_load_dwordx4 v[180:183], v8, s[88:89]
	global_load_dwordx4 v[184:187], v8, s[88:89] offset:16
	s_waitcnt vmcnt(0)
	v_lshlrev_b32_e32 v220, 16, v64
	v_and_b32_e32 v221, 0xffff0000, v64
	v_lshlrev_b32_e32 v222, 16, v65
	v_and_b32_e32 v223, 0xffff0000, v65
	v_lshlrev_b32_e32 v224, 16, v66
	v_and_b32_e32 v225, 0xffff0000, v66
	v_lshlrev_b32_e32 v226, 16, v67
	v_and_b32_e32 v227, 0xffff0000, v67
	v_mov_b32_e32 v228, v220
	v_mov_b32_e32 v229, v221
	v_mov_b32_e32 v230, v222
	v_mov_b32_e32 v231, v223
	v_mov_b32_e32 v232, v224
	v_mov_b32_e32 v233, v225
	v_mov_b32_e32 v234, v226
	v_mov_b32_e32 v235, v227
	v_add_f32_e32 v228, v228, v68
	v_add_f32_e32 v229, v229, v69
	v_add_f32_e32 v230, v230, v70
	v_add_f32_e32 v231, v231, v71
	v_add_f32_e32 v232, v232, v72
	v_add_f32_e32 v233, v233, v73
	v_add_f32_e32 v234, v234, v74
	v_add_f32_e32 v235, v235, v75
	v_add_f32_e32 v228, v228, v76
	v_add_f32_e32 v229, v229, v77
	v_add_f32_e32 v230, v230, v78
	v_add_f32_e32 v231, v231, v79
	v_add_f32_e32 v232, v232, v80
	v_add_f32_e32 v233, v233, v81
	v_add_f32_e32 v234, v234, v82
	v_add_f32_e32 v235, v235, v83
	v_add_f32_e32 v228, v228, v84
	v_add_f32_e32 v229, v229, v85
	v_add_f32_e32 v230, v230, v86
	v_add_f32_e32 v231, v231, v87
	v_add_f32_e32 v232, v232, v88
	v_add_f32_e32 v233, v233, v89
	v_add_f32_e32 v234, v234, v90
	v_add_f32_e32 v235, v235, v91
	v_add_f32_e32 v228, v228, v92
	v_add_f32_e32 v229, v229, v93
	v_add_f32_e32 v230, v230, v94
	v_add_f32_e32 v231, v231, v95
	v_add_f32_e32 v232, v232, v96
	v_add_f32_e32 v233, v233, v97
	v_add_f32_e32 v234, v234, v98
	v_add_f32_e32 v235, v235, v99
	v_add_f32_e32 v228, v228, v100
	v_add_f32_e32 v229, v229, v101
	v_add_f32_e32 v230, v230, v102
	v_add_f32_e32 v231, v231, v103
	v_add_f32_e32 v232, v232, v104
	v_add_f32_e32 v233, v233, v105
	v_add_f32_e32 v234, v234, v106
	v_add_f32_e32 v235, v235, v107
	v_add_f32_e32 v228, v228, v108
	v_add_f32_e32 v229, v229, v109
	v_add_f32_e32 v230, v230, v110
	v_add_f32_e32 v231, v231, v111
	v_add_f32_e32 v232, v232, v112
	v_add_f32_e32 v233, v233, v113
	v_add_f32_e32 v234, v234, v114
	v_add_f32_e32 v235, v235, v115
	v_add_f32_e32 v228, v228, v116
	v_add_f32_e32 v229, v229, v117
	v_add_f32_e32 v230, v230, v118
	v_add_f32_e32 v231, v231, v119
	v_add_f32_e32 v232, v232, v120
	v_add_f32_e32 v233, v233, v121
	v_add_f32_e32 v234, v234, v122
	v_add_f32_e32 v235, v235, v123
	v_add_f32_e32 v228, v228, v124
	v_add_f32_e32 v229, v229, v125
	v_add_f32_e32 v230, v230, v126
	v_add_f32_e32 v231, v231, v127
	v_add_f32_e32 v232, v232, v128
	v_add_f32_e32 v233, v233, v129
	v_add_f32_e32 v234, v234, v130
	v_add_f32_e32 v235, v235, v131
	v_add_f32_e32 v228, v228, v132
	v_add_f32_e32 v229, v229, v133
	v_add_f32_e32 v230, v230, v134
	v_add_f32_e32 v231, v231, v135
	v_add_f32_e32 v232, v232, v136
	v_add_f32_e32 v233, v233, v137
	v_add_f32_e32 v234, v234, v138
	v_add_f32_e32 v235, v235, v139
	v_add_f32_e32 v228, v228, v140
	v_add_f32_e32 v229, v229, v141
	v_add_f32_e32 v230, v230, v142
	v_add_f32_e32 v231, v231, v143
	v_add_f32_e32 v232, v232, v144
	v_add_f32_e32 v233, v233, v145
	v_add_f32_e32 v234, v234, v146
	v_add_f32_e32 v235, v235, v147
	v_add_f32_e32 v228, v228, v148
	v_add_f32_e32 v229, v229, v149
	v_add_f32_e32 v230, v230, v150
	v_add_f32_e32 v231, v231, v151
	v_add_f32_e32 v232, v232, v152
	v_add_f32_e32 v233, v233, v153
	v_add_f32_e32 v234, v234, v154
	v_add_f32_e32 v235, v235, v155
	v_add_f32_e32 v228, v228, v156
	v_add_f32_e32 v229, v229, v157
	v_add_f32_e32 v230, v230, v158
	v_add_f32_e32 v231, v231, v159
	v_add_f32_e32 v232, v232, v160
	v_add_f32_e32 v233, v233, v161
	v_add_f32_e32 v234, v234, v162
	v_add_f32_e32 v235, v235, v163
	v_add_f32_e32 v228, v228, v164
	v_add_f32_e32 v229, v229, v165
	v_add_f32_e32 v230, v230, v166
	v_add_f32_e32 v231, v231, v167
	v_add_f32_e32 v232, v232, v168
	v_add_f32_e32 v233, v233, v169
	v_add_f32_e32 v234, v234, v170
	v_add_f32_e32 v235, v235, v171
	v_add_f32_e32 v228, v228, v172
	v_add_f32_e32 v229, v229, v173
	v_add_f32_e32 v230, v230, v174
	v_add_f32_e32 v231, v231, v175
	v_add_f32_e32 v232, v232, v176
	v_add_f32_e32 v233, v233, v177
	v_add_f32_e32 v234, v234, v178
	v_add_f32_e32 v235, v235, v179
	v_add_f32_e32 v228, v228, v180
	v_add_f32_e32 v229, v229, v181
	v_add_f32_e32 v230, v230, v182
	v_add_f32_e32 v231, v231, v183
	v_add_f32_e32 v232, v232, v184
	v_add_f32_e32 v233, v233, v185
	v_add_f32_e32 v234, v234, v186
	v_add_f32_e32 v235, v235, v187
	v_mov_b32_e32 v48, 0x3d800000
	v_fma_f32 v228, v228, v48, -v220
	v_fma_f32 v229, v229, v48, -v221
	v_fma_f32 v230, v230, v48, -v222
	v_fma_f32 v231, v231, v48, -v223
	v_fma_f32 v232, v232, v48, -v224
	v_fma_f32 v233, v233, v48, -v225
	v_fma_f32 v234, v234, v48, -v226
	v_fma_f32 v235, v235, v48, -v227
	v_cvt_pk_bf16_f32 v244, v228, v229
	v_cvt_pk_bf16_f32 v245, v230, v231
	v_cvt_pk_bf16_f32 v246, v232, v233
	v_cvt_pk_bf16_f32 v247, v234, v235
	global_store_dwordx4 v7, v[244:247], s[84:85] offset:1536
	s_nop 1
.Lpoold_sg3_end:
.Lpoold_done:
.LBB0_661:
	s_or_b64 exec, exec, s[30:31]
	s_abs_i32 s3, s33
	v_cvt_f32_u32_e32 v0, s3
	s_mov_b32 s0, 0
	s_mov_b32 s77, -1
	v_mbcnt_lo_u32_b32 v1, -1, s0
	v_rcp_iflag_f32_e32 v0, v0
	v_mbcnt_hi_u32_b32 v1, -1, v1
	v_or_b32_e32 v208, s24, v1
	s_cmpk_gt_i32 s2, 0x7ff
	v_mul_f32_e32 v0, 0x4f7ffffe, v0
	v_cvt_u32_f32_e32 v0, v0
	s_nop 0
	v_readfirstlane_b32 s0, v0
	s_cbranch_scc1 .LBB0_786
	s_sub_i32 s1, 0, s3
	s_mul_i32 s1, s1, s0
	s_mov_b32 s7, 0
	s_mul_hi_u32 s1, s0, s1
	s_add_i32 s8, s0, s1
	s_mov_b32 s9, s7
	s_ashr_i32 s15, s33, 31
	s_lshl_b64 s[0:1], s[8:9], 11
	s_add_u32 s10, s22, 0x63a0000
	s_mul_i32 s0, s1, s3
	s_addc_u32 s11, s23, 0
	s_sub_i32 s0, 0x800, s0
	s_add_i32 s4, s1, 1
	s_sub_i32 s5, s0, s3
	s_cmp_ge_u32 s0, s3
	s_cselect_b32 s1, s4, s1
	s_cselect_b32 s0, s5, s0
	s_add_i32 s4, s1, 1
	s_cmp_ge_u32 s0, s3
	s_cselect_b32 s0, s4, s1
	s_xor_b32 s0, s0, s15
	s_sub_i32 s9, s0, s15
	s_mul_i32 s0, s9, s33
	s_cmpk_eq_i32 s0, 0x800
	s_cselect_b64 s[0:1], -1, 0
	s_add_u32 s25, s22, 0x17d2a000
	s_addc_u32 s38, s23, 0
	s_add_u32 s39, s22, 0x64a8000
	v_cndmask_b32_e64 v0, 0, 1, s[0:1]
	s_mul_i32 s9, s9, s2
	s_addc_u32 s40, s23, 0
	v_cmp_ne_u32_e64 s[0:1], 1, v0
	s_movk_i32 s41, 0x7f
	v_mov_b32_e32 v65, 0
	s_movk_i32 s42, 0x1ff
	s_add_i32 s43, 0, 0x1ca00
	s_movk_i32 s44, 0x1000
	s_movk_i32 s45, 0x2000
	s_movk_i32 s46, 0x3000
	s_movk_i32 s47, 0x4000
	s_add_i32 s48, 0, 0x1d200
	s_movk_i32 s49, 0x3ff
	s_movk_i32 s50, 0x4800
	s_add_i32 s51, 0, 0x1c8fc
	s_movk_i32 s56, 0x110
	s_movk_i32 s57, 0x84
	s_mov_b64 s[12:13], 0x4200
	s_mov_b32 s14, 0x358637bd
	s_mov_b32 s58, 0x800000
	s_movk_i32 s59, 0x4200
	s_add_i32 s60, 0, 0x4400
	s_movk_i32 s61, 0x100
	s_brev_b32 s66, 1
	s_movk_i32 s67, 0xfc00
	s_cmp_eq_u32 s32, 0
	s_cbranch_scc0 .Lcpd_first1
	s_lshr_b32 s4, s2, 2
	s_lshl_b32 s4, s4, 5
	s_and_b32 s5, s2, 3
	s_mul_i32 s5, s5, 6
	s_add_i32 s9, s4, s5
	s_branch .Lcpd_first_done
